# P4 epilogue: the next unit's seven row-sum loads issued inside the epilogue behind their consumers instead of behind the last store (next unit's first counted wait no longer covers the store tail)
# speedup vs baseline: 1.0027x; 1.0027x over previous
; __device__ __forceinline__ unsigned pkh7(float lo, float hi) { return (pkh(lo, hi) + 0x00080008u) & 0xFFF0FFF0u; }
;     __device__ __forceinline__ void operator()(const f32x4 (&acc)[2][2][4][2], const Unit& u, int wr, int wc, int fr_, int fq_) const {
;         int t_ = threadIdx.x; asm volatile("" : "+v"(t_)); const int fr = t_ & 15, fq = (t_ >> 4) & 3;
;         const int row0 = u.pm * BM + wr * 64 + fr; const int col0 = u.pn * HALF + wc * 32 + 8 * fq;
;         float rsv[2][4];
; #pragma unroll
;         for (int ai = 0; ai < 2; ++ai)
; #pragma unroll
;             for (int m = 0; m < 4; ++m) rsv[ai][m] = rowss[row0 + ai * HALF + m * 16];
; #pragma unroll
;         for (int ai = 0; ai < 2; ++ai)
; #pragma unroll
;             for (int m = 0; m < 4; ++m) {
;                 const int row = row0 + ai * HALF + m * 16;
;                 const float rs = __builtin_amdgcn_rsqf(rsv[ai][m] * (1.0f / D) + EPS);
;                 const float nrsl = -rs * LOG2E, irs2 = rsv[ai][m] * (1.0f / D) + EPS;
;                 f32x4 hv[2];
; #pragma unroll
;                 for (int n = 0; n < 2; ++n) {
;                     const f32x4 g = acc[ai][0][m][n], up = acc[ai][1][m][n];
;                     const f32x4 a = g * nrsl; f32x4 ex;
; #pragma unroll
;                     for (int e = 0; e < 4; ++e) ex[e] = __builtin_amdgcn_exp2f(a[e]);
;                     const f32x4 dn = ex * irs2 + irs2; f32x4 rc;
; #pragma unroll
;                     for (int e = 0; e < 4; ++e) rc[e] = __builtin_amdgcn_rcpf(dn[e]);
;                     hv[n] = (g * up) * rc;
;                 }
;                 u32x4 w; w.x = pkh7(hv[0][0], hv[0][1]); w.y = pkh7(hv[0][2], hv[0][3]); w.z = pkh7(hv[1][0], hv[1][1]); w.w = pkh7(hv[1][2], hv[1][3]);
;                 *(u32x4*)(Hd + (size_t)row * DFF + col0) = w;
;             }
.LBB0_853:
.LBB0_855:
	s_lshl_b32 s4, s46, 8
	v_mov_b32_e32 v144, v0
	s_add_i32 s4, s4, s30
	v_pk_mul_f32 v[142:143], v[106:107], v[118:119]
	v_and_or_b32 v132, v144, 15, s4
	v_ashrrev_i32_e32 v133, 31, v132
	v_lshl_add_u64 v[134:135], v[132:133], 2, s[0:1]
	v_or_b32_e32 v130, 16, v132
	v_ashrrev_i32_e32 v131, 31, v130
	v_lshl_add_u64 v[136:137], v[130:131], 2, s[0:1]
	v_lshrrev_b32_e32 v118, 1, v144
	v_or_b32_e32 v144, 32, v132
	v_pk_mul_f32 v[140:141], v[108:109], v[120:121]
	v_or_b32_e32 v120, 48, v132
	v_ashrrev_i32_e32 v145, 31, v144
	v_ashrrev_i32_e32 v121, 31, v120
	v_lshl_add_u64 v[146:147], v[144:145], 2, s[0:1]
	v_lshl_add_u64 v[148:149], v[120:121], 2, s[0:1]
	s_nop 0
	s_nop 0
	global_load_dword v121, v[134:135], off offset:704
	s_cmp_lg_u64 s[2:3], 0
	s_cselect_b32 s98, s40, s46
	s_lshl_b32 s98, s98, 8
	s_add_i32 s98, s98, s30
	v_and_or_b32 v160, v0, 15, s98
	v_mov_b32_e32 v161, 0
	v_lshl_add_u64 v[160:161], v[160:161], 2, s[0:1]
	v_pk_mul_f32 v[128:129], v[116:117], v[128:129]
	v_pk_mul_f32 v[126:127], v[114:115], v[126:127]
	v_pk_mul_f32 v[136:137], v[112:113], v[124:125]
	v_pk_mul_f32 v[138:139], v[110:111], v[122:123]
	s_lshl_b32 s4, s50, 7
	v_and_or_b32 v118, v118, 24, s4
	v_or_b32_e32 v118, s31, v118
	v_mov_b64_e32 v[122:123], s[18:19]
	v_ashrrev_i32_e32 v119, 31, v118
	v_add_u32_e32 v154, 0x80, v132
	v_add_u32_e32 v155, 0x90, v132
	v_add_u32_e32 v125, 0xa0, v132
	v_add_u32_e32 v124, 0xb0, v132
	v_mad_i64_i32 v[132:133], s[4:5], v132, s47, v[122:123]
	v_lshlrev_b64 v[118:119], 1, v[118:119]
	v_lshl_add_u64 v[132:133], v[132:133], 0, v[118:119]
	s_andn2_b64 vcc, exec, s[2:3]
	s_mov_b64 s[2:3], -1
	s_cmp_lg_u64 s[36:37], 0
	s_cbranch_scc0 .Lepi_nobar_p4
	s_barrier
.Lepi_nobar_p4:
	v_fmamk_f32 v134, v248, 0x3a800000, v215
	global_load_dword v248, v[160:161], off
	v_rsq_f32_e32 v135, v134
	v_fmamk_f32 v146, v249, 0x3a800000, v215
	global_load_dword v249, v[160:161], off offset:64
	v_rsq_f32_e32 v131, v146
	v_mul_f32_e32 v148, 0xbfb8aa3b, v135
	v_pk_mul_f32 v[116:117], v[116:117], v[148:149] op_sel_hi:[1,0]
	v_pk_mul_f32 v[114:115], v[114:115], v[148:149] op_sel_hi:[1,0]
	v_pk_mul_f32 v[112:113], v[112:113], v[148:149] op_sel_hi:[1,0]
	v_pk_mul_f32 v[110:111], v[110:111], v[148:149] op_sel_hi:[1,0]
	v_exp_f32_e32 v114, v114
	v_exp_f32_e32 v115, v115
	v_exp_f32_e32 v116, v116
	v_exp_f32_e32 v117, v117
	v_exp_f32_e32 v110, v110
	v_exp_f32_e32 v111, v111
	v_exp_f32_e32 v112, v112
	v_exp_f32_e32 v113, v113
	v_mul_f32_e32 v148, 0xbfb8aa3b, v131
	v_pk_mul_f32 v[108:109], v[108:109], v[148:149] op_sel_hi:[1,0]
	v_pk_mul_f32 v[106:107], v[106:107], v[148:149] op_sel_hi:[1,0]
	v_exp_f32_e32 v108, v108
	v_exp_f32_e32 v106, v106
	v_exp_f32_e32 v107, v107
	v_exp_f32_e32 v109, v109
	v_pk_fma_f32 v[116:117], v[134:135], v[116:117], v[134:135] op_sel_hi:[0,1,0]
	v_pk_fma_f32 v[114:115], v[134:135], v[114:115], v[134:135] op_sel_hi:[0,1,0]
	v_pk_fma_f32 v[112:113], v[134:135], v[112:113], v[134:135] op_sel_hi:[0,1,0]
	v_pk_fma_f32 v[110:111], v[134:135], v[110:111], v[134:135] op_sel_hi:[0,1,0]
	v_rcp_f32_e32 v114, v114
	v_rcp_f32_e32 v115, v115
	v_rcp_f32_e32 v116, v116
	v_rcp_f32_e32 v117, v117
	v_rcp_f32_e32 v110, v110
	v_rcp_f32_e32 v111, v111
	v_rcp_f32_e32 v112, v112
	v_rcp_f32_e32 v113, v113
	v_pk_fma_f32 v[108:109], v[146:147], v[108:109], v[146:147] op_sel_hi:[0,1,0]
	v_pk_fma_f32 v[106:107], v[146:147], v[106:107], v[146:147] op_sel_hi:[0,1,0]
	v_rcp_f32_e32 v134, v106
	v_rcp_f32_e32 v135, v107
	v_rcp_f32_e32 v152, v108
	v_rcp_f32_e32 v153, v109
	v_pk_mul_f32 v[106:107], v[128:129], v[116:117]
	v_pk_mul_f32 v[108:109], v[126:127], v[114:115]
	v_pk_mul_f32 v[112:113], v[136:137], v[112:113]
	v_pk_mul_f32 v[110:111], v[138:139], v[110:111]
	v_cvt_pk_f16_f32 v108, v108, v109
	v_cvt_pk_f16_f32 v106, v106, v107
	v_cvt_pk_f16_f32 v107, v110, v111
	v_cvt_pk_f16_f32 v109, v112, v113
	v_add_u32_e32 v108, 0x80008, v108
	v_add_u32_e32 v110, 0x80008, v106
	v_add_u32_e32 v111, 0x80008, v107
	v_add_u32_e32 v109, 0x80008, v109
	v_pk_mul_f32 v[150:151], v[100:101], v[148:149] op_sel_hi:[1,0]
	v_pk_mul_f32 v[148:149], v[98:99], v[148:149] op_sel_hi:[1,0]
	v_and_b32_e32 v106, 0xfff0fff0, v108
	v_and_b32_e32 v107, 0xfff0fff0, v110
	v_and_b32_e32 v108, 0xfff0fff0, v111
	v_and_b32_e32 v109, 0xfff0fff0, v109
	v_exp_f32_e32 v148, v148
	global_store_dwordx4 v[132:133], v[106:109], off
	v_exp_f32_e32 v149, v149
	v_pk_mul_f32 v[100:101], v[100:101], v[104:105]
	v_exp_f32_e32 v106, v150
	v_exp_f32_e32 v107, v151
	v_pk_fma_f32 v[112:113], v[146:147], v[148:149], v[146:147] op_sel_hi:[0,1,0]
	v_rcp_f32_e32 v112, v112
	v_rcp_f32_e32 v113, v113
	v_pk_fma_f32 v[106:107], v[146:147], v[106:107], v[146:147] op_sel_hi:[0,1,0]
	v_rcp_f32_e32 v106, v106
	v_rcp_f32_e32 v107, v107
	v_pk_mul_f32 v[98:99], v[98:99], v[102:103]
	v_pk_mul_f32 v[108:109], v[140:141], v[152:153]
	v_pk_mul_f32 v[110:111], v[142:143], v[134:135]
	v_pk_mul_f32 v[102:103], v[100:101], v[106:107]
	v_pk_mul_f32 v[100:101], v[98:99], v[112:113]
	v_cvt_pk_f16_f32 v98, v110, v111
	v_cvt_pk_f16_f32 v100, v100, v101
	v_cvt_pk_f16_f32 v101, v102, v103
	v_fmamk_f32 v102, v253, 0x3a800000, v215
	global_load_dword v253, v[160:161], off offset:128
	v_rsq_f32_e32 v103, v102
	v_cvt_pk_f16_f32 v99, v108, v109
	v_add_u32_e32 v98, 0x80008, v98
	v_add_u32_e32 v99, 0x80008, v99
	v_mul_f32_e32 v106, 0xbfb8aa3b, v103
	v_pk_mul_f32 v[108:109], v[92:93], v[106:107] op_sel_hi:[1,0]
	v_pk_mul_f32 v[110:111], v[90:91], v[106:107] op_sel_hi:[1,0]
	v_pk_mul_f32 v[92:93], v[92:93], v[96:97]
	v_pk_mul_f32 v[90:91], v[90:91], v[94:95]
	v_pk_mul_f32 v[94:95], v[84:85], v[106:107] op_sel_hi:[1,0]
; __device__ __forceinline__ unsigned pkh7(float lo, float hi) { return (pkh(lo, hi) + 0x00080008u) & 0xFFF0FFF0u; }
;     __device__ __forceinline__ void operator()(const f32x4 (&acc)[2][2][4][2], const Unit& u, int wr, int wc, int fr_, int fq_) const {
;     ...
;         for (int ai = 0; ai < 2; ++ai)
; #pragma unroll
;             for (int m = 0; m < 4; ++m) {
;                 const int row = row0 + ai * HALF + m * 16;
;                 const float rs = __builtin_amdgcn_rsqf(rsv[ai][m] * (1.0f / D) + EPS);
;                 const float nrsl = -rs * LOG2E, irs2 = rsv[ai][m] * (1.0f / D) + EPS;
;                 f32x4 hv[2];
; #pragma unroll
;                 for (int n = 0; n < 2; ++n) {
;                     const f32x4 g = acc[ai][0][m][n], up = acc[ai][1][m][n];
;                     const f32x4 a = g * nrsl; f32x4 ex;
; #pragma unroll
;                     for (int e = 0; e < 4; ++e) ex[e] = __builtin_amdgcn_exp2f(a[e]);
;                     const f32x4 dn = ex * irs2 + irs2; f32x4 rc;
; #pragma unroll
;                     for (int e = 0; e < 4; ++e) rc[e] = __builtin_amdgcn_rcpf(dn[e]);
;                     hv[n] = (g * up) * rc;
;                 }
;                 u32x4 w; w.x = pkh7(hv[0][0], hv[0][1]); w.y = pkh7(hv[0][2], hv[0][3]); w.z = pkh7(hv[1][0], hv[1][1]); w.w = pkh7(hv[1][2], hv[1][3]);
;                 *(u32x4*)(Hd + (size_t)row * DFF + col0) = w;
;             }
	v_pk_mul_f32 v[96:97], v[82:83], v[106:107] op_sel_hi:[1,0]
	v_exp_f32_e32 v94, v94
	v_exp_f32_e32 v96, v96
	v_exp_f32_e32 v95, v95
	v_exp_f32_e32 v97, v97
	v_exp_f32_e32 v110, v110
	v_exp_f32_e32 v111, v111
	v_pk_fma_f32 v[94:95], v[102:103], v[94:95], v[102:103] op_sel_hi:[0,1,0]
	v_pk_fma_f32 v[96:97], v[102:103], v[96:97], v[102:103] op_sel_hi:[0,1,0]
	v_rcp_f32_e32 v96, v96
	v_rcp_f32_e32 v94, v94
	v_rcp_f32_e32 v95, v95
	v_rcp_f32_e32 v97, v97
	v_exp_f32_e32 v108, v108
	v_exp_f32_e32 v109, v109
	v_add_u32_e32 v100, 0x80008, v100
	v_add_u32_e32 v101, 0x80008, v101
	v_mad_i64_i32 v[104:105], s[4:5], v130, s47, v[122:123]
	v_and_b32_e32 v98, 0xfff0fff0, v98
	v_and_b32_e32 v99, 0xfff0fff0, v99
	v_and_b32_e32 v100, 0xfff0fff0, v100
	v_and_b32_e32 v101, 0xfff0fff0, v101
	v_lshl_add_u64 v[104:105], v[104:105], 0, v[118:119]
	v_pk_mul_f32 v[84:85], v[84:85], v[88:89]
	v_pk_mul_f32 v[82:83], v[82:83], v[86:87]
	global_store_dwordx4 v[104:105], v[98:101], off
	v_pk_mul_f32 v[86:87], v[84:85], v[94:95]
	v_pk_mul_f32 v[84:85], v[82:83], v[96:97]
	v_pk_fma_f32 v[100:101], v[102:103], v[110:111], v[102:103] op_sel_hi:[0,1,0]
	v_pk_fma_f32 v[98:99], v[102:103], v[108:109], v[102:103] op_sel_hi:[0,1,0]
	v_rcp_f32_e32 v100, v100
	v_rcp_f32_e32 v101, v101
	v_cvt_pk_f16_f32 v84, v84, v85
	v_cvt_pk_f16_f32 v85, v86, v87
	v_fmamk_f32 v86, v255, 0x3a800000, v215
	global_load_dword v255, v[160:161], off offset:192
	v_rcp_f32_e32 v98, v98
	v_rcp_f32_e32 v99, v99
	v_rsq_f32_e32 v87, v86
	v_pk_mul_f32 v[90:91], v[90:91], v[100:101]
	v_add_u32_e32 v84, 0x80008, v84
	v_pk_mul_f32 v[92:93], v[92:93], v[98:99]
	v_cvt_pk_f16_f32 v82, v90, v91
	v_mul_f32_e32 v90, 0xbfb8aa3b, v87
	v_cvt_pk_f16_f32 v83, v92, v93
	v_pk_mul_f32 v[92:93], v[76:77], v[90:91] op_sel_hi:[1,0]
	v_pk_mul_f32 v[94:95], v[74:75], v[90:91] op_sel_hi:[1,0]
	v_pk_mul_f32 v[76:77], v[76:77], v[80:81]
	v_pk_mul_f32 v[74:75], v[74:75], v[78:79]
	v_pk_mul_f32 v[78:79], v[64:65], v[90:91] op_sel_hi:[1,0]
	v_pk_mul_f32 v[80:81], v[62:63], v[90:91] op_sel_hi:[1,0]
	v_exp_f32_e32 v78, v78
	v_exp_f32_e32 v80, v80
	v_exp_f32_e32 v79, v79
	v_exp_f32_e32 v81, v81
	v_exp_f32_e32 v94, v94
	v_exp_f32_e32 v95, v95
	v_pk_fma_f32 v[78:79], v[86:87], v[78:79], v[86:87] op_sel_hi:[0,1,0]
	v_pk_fma_f32 v[80:81], v[86:87], v[80:81], v[86:87] op_sel_hi:[0,1,0]
	v_rcp_f32_e32 v80, v80
	v_rcp_f32_e32 v78, v78
	v_rcp_f32_e32 v79, v79
	v_rcp_f32_e32 v81, v81
	v_exp_f32_e32 v92, v92
	v_exp_f32_e32 v93, v93
	v_add_u32_e32 v82, 0x80008, v82
	v_add_u32_e32 v83, 0x80008, v83
	v_add_u32_e32 v85, 0x80008, v85
	v_mad_i64_i32 v[88:89], s[4:5], v144, s47, v[122:123]
	v_and_b32_e32 v82, 0xfff0fff0, v82
	v_and_b32_e32 v83, 0xfff0fff0, v83
	v_and_b32_e32 v84, 0xfff0fff0, v84
	v_and_b32_e32 v85, 0xfff0fff0, v85
	v_lshl_add_u64 v[88:89], v[88:89], 0, v[118:119]
	v_pk_mul_f32 v[64:65], v[64:65], v[72:73]
	v_pk_mul_f32 v[62:63], v[62:63], v[70:71]
	global_store_dwordx4 v[88:89], v[82:85], off
	v_pk_mul_f32 v[70:71], v[64:65], v[78:79]
	v_pk_mul_f32 v[64:65], v[62:63], v[80:81]
	v_pk_fma_f32 v[84:85], v[86:87], v[94:95], v[86:87] op_sel_hi:[0,1,0]
	v_pk_fma_f32 v[82:83], v[86:87], v[92:93], v[86:87] op_sel_hi:[0,1,0]
	v_rcp_f32_e32 v84, v84
	v_rcp_f32_e32 v85, v85
	v_cvt_pk_f16_f32 v64, v64, v65
	v_cvt_pk_f16_f32 v65, v70, v71
	v_fmamk_f32 v70, v250, 0x3a800000, v215
	global_load_dword v250, v[160:161], off offset:512
	v_rcp_f32_e32 v82, v82
	v_rcp_f32_e32 v83, v83
	v_rsq_f32_e32 v71, v70
	v_pk_mul_f32 v[74:75], v[74:75], v[84:85]
	v_add_u32_e32 v64, 0x80008, v64
	v_pk_mul_f32 v[76:77], v[76:77], v[82:83]
	v_cvt_pk_f16_f32 v62, v74, v75
	v_mul_f32_e32 v74, 0xbfb8aa3b, v71
	v_cvt_pk_f16_f32 v63, v76, v77
	v_pk_mul_f32 v[76:77], v[60:61], v[74:75] op_sel_hi:[1,0]
	v_pk_mul_f32 v[78:79], v[58:59], v[74:75] op_sel_hi:[1,0]
	v_exp_f32_e32 v76, v76
	v_exp_f32_e32 v78, v78
	v_exp_f32_e32 v77, v77
	v_exp_f32_e32 v79, v79
	v_add_u32_e32 v62, 0x80008, v62
	v_add_u32_e32 v63, 0x80008, v63
	v_add_u32_e32 v65, 0x80008, v65
	v_mad_i64_i32 v[72:73], s[4:5], v120, s47, v[122:123]
	v_and_b32_e32 v62, 0xfff0fff0, v62
	v_and_b32_e32 v63, 0xfff0fff0, v63
	v_and_b32_e32 v64, 0xfff0fff0, v64
	v_and_b32_e32 v65, 0xfff0fff0, v65
	v_lshl_add_u64 v[72:73], v[72:73], 0, v[118:119]
	global_store_dwordx4 v[72:73], v[62:65], off
	v_pk_mul_f32 v[60:61], v[60:61], v[68:69]
	v_pk_mul_f32 v[58:59], v[58:59], v[66:67]
	v_pk_fma_f32 v[62:63], v[70:71], v[76:77], v[70:71] op_sel_hi:[0,1,0]
	v_pk_fma_f32 v[64:65], v[70:71], v[78:79], v[70:71] op_sel_hi:[0,1,0]
	v_pk_mul_f32 v[66:67], v[52:53], v[74:75] op_sel_hi:[1,0]
	v_pk_mul_f32 v[68:69], v[50:51], v[74:75] op_sel_hi:[1,0]
	v_rcp_f32_e32 v64, v64
	v_rcp_f32_e32 v65, v65
	v_rcp_f32_e32 v62, v62
	v_rcp_f32_e32 v63, v63
	v_exp_f32_e32 v68, v68
	v_exp_f32_e32 v66, v66
	v_exp_f32_e32 v67, v67
	v_exp_f32_e32 v69, v69
	v_pk_mul_f32 v[60:61], v[60:61], v[62:63]
	v_pk_mul_f32 v[58:59], v[58:59], v[64:65]
	v_pk_fma_f32 v[62:63], v[70:71], v[66:67], v[70:71] op_sel_hi:[0,1,0]
	v_pk_fma_f32 v[64:65], v[70:71], v[68:69], v[70:71] op_sel_hi:[0,1,0]
	v_rcp_f32_e32 v64, v64
	v_rcp_f32_e32 v62, v62
	v_rcp_f32_e32 v63, v63
	v_rcp_f32_e32 v65, v65
	v_pk_mul_f32 v[52:53], v[52:53], v[56:57]
	v_pk_mul_f32 v[50:51], v[50:51], v[54:55]
	v_pk_mul_f32 v[54:55], v[52:53], v[62:63]
	v_pk_mul_f32 v[52:53], v[50:51], v[64:65]
	v_cvt_pk_f16_f32 v50, v58, v59
	v_cvt_pk_f16_f32 v52, v52, v53
	v_cvt_pk_f16_f32 v53, v54, v55
	v_fmamk_f32 v54, v251, 0x3a800000, v215
	global_load_dword v251, v[160:161], off offset:576
	v_rsq_f32_e32 v55, v54
	v_cvt_pk_f16_f32 v51, v60, v61
	v_add_u32_e32 v50, 0x80008, v50
	v_add_u32_e32 v51, 0x80008, v51
; __device__ __forceinline__ unsigned pkh7(float lo, float hi) { return (pkh(lo, hi) + 0x00080008u) & 0xFFF0FFF0u; }
; #define PG8_BAR __builtin_amdgcn_s_barrier()
;     __device__ __forceinline__ void operator()(const f32x4 (&acc)[2][2][4][2], const Unit& u, int wr, int wc, int fr_, int fq_) const {
;     ...
;             for (int m = 0; m < 4; ++m) {
;                 const int row = row0 + ai * HALF + m * 16;
;                 const float rs = __builtin_amdgcn_rsqf(rsv[ai][m] * (1.0f / D) + EPS);
;                 const float nrsl = -rs * LOG2E, irs2 = rsv[ai][m] * (1.0f / D) + EPS;
;                 f32x4 hv[2];
; #pragma unroll
;                 for (int n = 0; n < 2; ++n) {
;                     const f32x4 g = acc[ai][0][m][n], up = acc[ai][1][m][n];
;                     const f32x4 a = g * nrsl; f32x4 ex;
; #pragma unroll
;                     for (int e = 0; e < 4; ++e) ex[e] = __builtin_amdgcn_exp2f(a[e]);
;                     const f32x4 dn = ex * irs2 + irs2; f32x4 rc;
; #pragma unroll
;                     for (int e = 0; e < 4; ++e) rc[e] = __builtin_amdgcn_rcpf(dn[e]);
;                     hv[n] = (g * up) * rc;
;                 }
;                 u32x4 w; w.x = pkh7(hv[0][0], hv[0][1]); w.y = pkh7(hv[0][2], hv[0][3]); w.z = pkh7(hv[1][0], hv[1][1]); w.w = pkh7(hv[1][2], hv[1][3]);
;                 *(u32x4*)(Hd + (size_t)row * DFF + col0) = w;
;             }
;     ...
;         if constexpr (!Epi::AFTER_DRAIN) { E(acc, cur, wr, wc, fr, fq); S.done(cur); }
;         if (!has_next) break;
;         if constexpr (!SP2) {
; #pragma unroll
;         for (int a = 0; a < 2; ++a)
; #pragma unroll
;             for (int b = 0; b < 2; ++b)
; #pragma unroll
;                 for (int m = 0; m < 4; ++m)
; #pragma unroll
;                     for (int n = 0; n < 2; ++n) acc[a][b][m][n] = (f32x4){0.f, 0.f, 0.f, 0.f};
;         }
;         cur = nxt; cA = nA; cB = nB; ++ui;
;         if constexpr (ALIGN_EPI) { if (wr == 1) PG8_BAR; }
;     }
	v_mul_f32_e32 v58, 0xbfb8aa3b, v55
	v_pk_mul_f32 v[60:61], v[44:45], v[58:59] op_sel_hi:[1,0]
	v_pk_mul_f32 v[62:63], v[42:43], v[58:59] op_sel_hi:[1,0]
	v_pk_mul_f32 v[44:45], v[44:45], v[48:49]
	v_pk_mul_f32 v[42:43], v[42:43], v[46:47]
	v_pk_mul_f32 v[46:47], v[36:37], v[58:59] op_sel_hi:[1,0]
	v_pk_mul_f32 v[48:49], v[34:35], v[58:59] op_sel_hi:[1,0]
	v_exp_f32_e32 v46, v46
	v_exp_f32_e32 v48, v48
	v_exp_f32_e32 v47, v47
	v_exp_f32_e32 v49, v49
	v_exp_f32_e32 v62, v62
	v_exp_f32_e32 v63, v63
	v_pk_fma_f32 v[46:47], v[54:55], v[46:47], v[54:55] op_sel_hi:[0,1,0]
	v_pk_fma_f32 v[48:49], v[54:55], v[48:49], v[54:55] op_sel_hi:[0,1,0]
	v_rcp_f32_e32 v48, v48
	v_rcp_f32_e32 v46, v46
	v_rcp_f32_e32 v47, v47
	v_rcp_f32_e32 v49, v49
	v_exp_f32_e32 v60, v60
	v_exp_f32_e32 v61, v61
	v_add_u32_e32 v52, 0x80008, v52
	v_add_u32_e32 v53, 0x80008, v53
	v_mad_i64_i32 v[56:57], s[4:5], v154, s47, v[122:123]
	v_and_b32_e32 v50, 0xfff0fff0, v50
	v_and_b32_e32 v51, 0xfff0fff0, v51
	v_and_b32_e32 v52, 0xfff0fff0, v52
	v_and_b32_e32 v53, 0xfff0fff0, v53
	v_lshl_add_u64 v[56:57], v[56:57], 0, v[118:119]
	v_pk_mul_f32 v[36:37], v[36:37], v[40:41]
	v_pk_mul_f32 v[34:35], v[34:35], v[38:39]
	global_store_dwordx4 v[56:57], v[50:53], off
	v_pk_mul_f32 v[38:39], v[36:37], v[46:47]
	v_pk_mul_f32 v[36:37], v[34:35], v[48:49]
	v_pk_fma_f32 v[52:53], v[54:55], v[62:63], v[54:55] op_sel_hi:[0,1,0]
	v_pk_fma_f32 v[50:51], v[54:55], v[60:61], v[54:55] op_sel_hi:[0,1,0]
	v_rcp_f32_e32 v52, v52
	v_rcp_f32_e32 v53, v53
	v_cvt_pk_f16_f32 v36, v36, v37
	v_cvt_pk_f16_f32 v37, v38, v39
	v_fmamk_f32 v38, v252, 0x3a800000, v215
	global_load_dword v252, v[160:161], off offset:640
	v_rcp_f32_e32 v50, v50
	v_rcp_f32_e32 v51, v51
	v_rsq_f32_e32 v39, v38
	v_pk_mul_f32 v[42:43], v[42:43], v[52:53]
	v_add_u32_e32 v36, 0x80008, v36
	v_pk_mul_f32 v[44:45], v[44:45], v[50:51]
	v_cvt_pk_f16_f32 v34, v42, v43
	v_mul_f32_e32 v42, 0xbfb8aa3b, v39
	v_cvt_pk_f16_f32 v35, v44, v45
	v_pk_mul_f32 v[44:45], v[28:29], v[42:43] op_sel_hi:[1,0]
	v_pk_mul_f32 v[46:47], v[26:27], v[42:43] op_sel_hi:[1,0]
	v_pk_mul_f32 v[28:29], v[28:29], v[32:33]
	v_pk_mul_f32 v[26:27], v[26:27], v[30:31]
	v_pk_mul_f32 v[30:31], v[20:21], v[42:43] op_sel_hi:[1,0]
	v_pk_mul_f32 v[32:33], v[18:19], v[42:43] op_sel_hi:[1,0]
	v_exp_f32_e32 v30, v30
	v_exp_f32_e32 v32, v32
	v_exp_f32_e32 v31, v31
	v_exp_f32_e32 v33, v33
	v_exp_f32_e32 v46, v46
	v_exp_f32_e32 v47, v47
	v_pk_fma_f32 v[30:31], v[38:39], v[30:31], v[38:39] op_sel_hi:[0,1,0]
	v_pk_fma_f32 v[32:33], v[38:39], v[32:33], v[38:39] op_sel_hi:[0,1,0]
	v_rcp_f32_e32 v32, v32
	v_rcp_f32_e32 v30, v30
	v_rcp_f32_e32 v31, v31
	v_rcp_f32_e32 v33, v33
	v_exp_f32_e32 v44, v44
	v_exp_f32_e32 v45, v45
	v_add_u32_e32 v34, 0x80008, v34
	v_add_u32_e32 v35, 0x80008, v35
	v_add_u32_e32 v37, 0x80008, v37
	v_mad_i64_i32 v[40:41], s[4:5], v155, s47, v[122:123]
	v_and_b32_e32 v34, 0xfff0fff0, v34
	v_and_b32_e32 v35, 0xfff0fff0, v35
	v_and_b32_e32 v36, 0xfff0fff0, v36
	v_and_b32_e32 v37, 0xfff0fff0, v37
	v_lshl_add_u64 v[40:41], v[40:41], 0, v[118:119]
	v_pk_mul_f32 v[20:21], v[20:21], v[24:25]
	v_pk_mul_f32 v[18:19], v[18:19], v[22:23]
	global_store_dwordx4 v[40:41], v[34:37], off
	v_pk_mul_f32 v[22:23], v[20:21], v[30:31]
	v_pk_mul_f32 v[20:21], v[18:19], v[32:33]
	v_pk_fma_f32 v[36:37], v[38:39], v[46:47], v[38:39] op_sel_hi:[0,1,0]
	v_pk_fma_f32 v[34:35], v[38:39], v[44:45], v[38:39] op_sel_hi:[0,1,0]
	v_rcp_f32_e32 v36, v36
	v_rcp_f32_e32 v37, v37
	v_cvt_pk_f16_f32 v20, v20, v21
	v_cvt_pk_f16_f32 v21, v22, v23
	s_waitcnt vmcnt(13)
	v_fmamk_f32 v22, v121, 0x3a800000, v215
	v_rcp_f32_e32 v34, v34
	v_rcp_f32_e32 v35, v35
	v_rsq_f32_e32 v23, v22
	v_pk_mul_f32 v[26:27], v[26:27], v[36:37]
	v_add_u32_e32 v20, 0x80008, v20
	v_pk_mul_f32 v[28:29], v[28:29], v[34:35]
	v_cvt_pk_f16_f32 v18, v26, v27
	v_mul_f32_e32 v26, 0xbfb8aa3b, v23
	v_cvt_pk_f16_f32 v19, v28, v29
	v_pk_mul_f32 v[28:29], v[12:13], v[26:27] op_sel_hi:[1,0]
	v_pk_mul_f32 v[30:31], v[10:11], v[26:27] op_sel_hi:[1,0]
	v_pk_mul_f32 v[12:13], v[12:13], v[16:17]
	v_pk_mul_f32 v[10:11], v[10:11], v[14:15]
	v_pk_mul_f32 v[14:15], v[4:5], v[26:27] op_sel_hi:[1,0]
	v_pk_mul_f32 v[16:17], v[2:3], v[26:27] op_sel_hi:[1,0]
	v_exp_f32_e32 v30, v30
	v_exp_f32_e32 v28, v28
	v_exp_f32_e32 v29, v29
	v_exp_f32_e32 v31, v31
	v_exp_f32_e32 v16, v16
	v_exp_f32_e32 v14, v14
	v_exp_f32_e32 v15, v15
	v_exp_f32_e32 v17, v17
	v_add_u32_e32 v18, 0x80008, v18
	v_add_u32_e32 v19, 0x80008, v19
	v_add_u32_e32 v21, 0x80008, v21
	v_mad_i64_i32 v[24:25], s[4:5], v125, s47, v[122:123]
	v_and_b32_e32 v18, 0xfff0fff0, v18
	v_and_b32_e32 v19, 0xfff0fff0, v19
	v_and_b32_e32 v20, 0xfff0fff0, v20
	v_and_b32_e32 v21, 0xfff0fff0, v21
	v_lshl_add_u64 v[24:25], v[24:25], 0, v[118:119]
	global_store_dwordx4 v[24:25], v[18:21], off
	v_pk_fma_f32 v[14:15], v[22:23], v[14:15], v[22:23] op_sel_hi:[0,1,0]
	v_pk_fma_f32 v[16:17], v[22:23], v[16:17], v[22:23] op_sel_hi:[0,1,0]
	v_pk_fma_f32 v[18:19], v[22:23], v[28:29], v[22:23] op_sel_hi:[0,1,0]
	v_pk_fma_f32 v[20:21], v[22:23], v[30:31], v[22:23] op_sel_hi:[0,1,0]
	v_rcp_f32_e32 v20, v20
	v_rcp_f32_e32 v21, v21
	v_rcp_f32_e32 v18, v18
	v_rcp_f32_e32 v19, v19
	v_rcp_f32_e32 v16, v16
	v_rcp_f32_e32 v14, v14
	v_rcp_f32_e32 v15, v15
	v_rcp_f32_e32 v17, v17
	v_pk_mul_f32 v[4:5], v[4:5], v[8:9]
	v_pk_mul_f32 v[2:3], v[2:3], v[6:7]
	v_pk_mul_f32 v[12:13], v[12:13], v[18:19]
	v_pk_mul_f32 v[10:11], v[10:11], v[20:21]
	v_pk_mul_f32 v[6:7], v[4:5], v[14:15]
	v_pk_mul_f32 v[4:5], v[2:3], v[16:17]
	v_cvt_pk_f16_f32 v2, v10, v11
	v_cvt_pk_f16_f32 v3, v12, v13
	v_cvt_pk_f16_f32 v4, v4, v5
	v_cvt_pk_f16_f32 v5, v6, v7
	v_add_u32_e32 v2, 0x80008, v2
	v_add_u32_e32 v3, 0x80008, v3
	v_add_u32_e32 v4, 0x80008, v4
	v_add_u32_e32 v5, 0x80008, v5
	v_mad_i64_i32 v[6:7], s[4:5], v124, s47, v[122:123]
	v_and_b32_e32 v2, 0xfff0fff0, v2
	v_and_b32_e32 v3, 0xfff0fff0, v3
	v_and_b32_e32 v4, 0xfff0fff0, v4
	v_and_b32_e32 v5, 0xfff0fff0, v5
	v_lshl_add_u64 v[6:7], v[6:7], 0, v[118:119]
	global_store_dwordx4 v[6:7], v[2:5], off
	s_cbranch_vccnz .LBB0_838
	s_andn2_b64 vcc, exec, s[20:21]
	s_cbranch_vccnz .LBB0_837
	s_barrier
	s_branch .LBB0_837
